# speedup vs baseline: 1.0051x; 1.0051x over previous
.LBB0_440:
	s_mov_b32 s5, 0xfffee000
	v_add_co_u32_e64 v8, s[8:9], s5, v16
	v_add_u32_e32 v84, s4, v77
	s_nop 0
	v_addc_co_u32_e64 v9, s[8:9], -1, v17, s[8:9]
	global_load_dwordx4 v[8:11], v[8:9], off nt
	s_mov_b32 s5, 0xffff4000
	v_add_co_u32_e64 v114, s[8:9], s5, v16
	s_nop 1
	v_addc_co_u32_e64 v115, s[8:9], -1, v17, s[8:9]
	global_load_dwordx4 v[100:103], v[114:115], off nt
	s_movk_i32 s5, 0xa000
	v_add_co_u32_e64 v116, s[8:9], s5, v16
	s_nop 1
	v_addc_co_u32_e64 v117, s[8:9], -1, v17, s[8:9]
	global_load_dwordx4 v[104:107], v[116:117], off nt
	global_load_dwordx4 v[108:111], v[16:17], off nt
	ds_read_b128 v[38:41], v84
	ds_read_b128 v[42:45], v84 offset:8192
	ds_read_b128 v[46:49], v84 offset:16384
	ds_read_b128 v[50:53], v84 offset:24576
	ds_read_b128 v[54:57], v84 offset:32768
	ds_read_b128 v[58:61], v84 offset:40960
	v_add_u32_e32 v88, 0x10000, v84
	s_add_i32 s4, s4, 16
	s_cmpk_lg_i32 s4, 0x200
	s_waitcnt vmcnt(3) lgkmcnt(5)
	v_pk_fma_f32 v[34:35], v[8:9], v[38:39], v[66:67] op_sel_hi:[1,0,1]
	v_pk_fma_f32 v[62:63], v[10:11], v[38:39], v[72:73] op_sel_hi:[1,0,1]
	s_waitcnt lgkmcnt(4)
	v_pk_fma_f32 v[74:75], v[8:9], v[42:43], v[68:69] op_sel_hi:[1,0,1]
	v_pk_fma_f32 v[82:83], v[10:11], v[42:43], v[70:71] op_sel_hi:[1,0,1]
	ds_read_b128 v[66:69], v84 offset:49152
	ds_read_b128 v[70:73], v84 offset:57344
	s_waitcnt lgkmcnt(5)
	v_pk_fma_f32 v[64:65], v[8:9], v[46:47], v[64:65] op_sel_hi:[1,0,1]
	v_pk_fma_f32 v[36:37], v[10:11], v[46:47], v[36:37] op_sel_hi:[1,0,1]
	s_waitcnt lgkmcnt(4)
	v_pk_fma_f32 v[30:31], v[8:9], v[50:51], v[30:31] op_sel_hi:[1,0,1]
	v_pk_fma_f32 v[32:33], v[10:11], v[50:51], v[32:33] op_sel_hi:[1,0,1]
	s_waitcnt lgkmcnt(0)
	v_pk_fma_f32 v[84:85], v[8:9], v[70:71], v[0:1] op_sel_hi:[1,0,1]
	v_pk_fma_f32 v[86:87], v[10:11], v[70:71], v[2:3] op_sel_hi:[1,0,1]
	ds_read_b128 v[0:3], v88
	v_pk_fma_f32 v[26:27], v[8:9], v[54:55], v[26:27] op_sel_hi:[1,0,1]
	v_pk_fma_f32 v[28:29], v[10:11], v[54:55], v[28:29] op_sel_hi:[1,0,1]
	v_pk_fma_f32 v[22:23], v[8:9], v[58:59], v[22:23] op_sel_hi:[1,0,1]
	v_pk_fma_f32 v[24:25], v[10:11], v[58:59], v[24:25] op_sel_hi:[1,0,1]
	s_waitcnt lgkmcnt(0)
	v_pk_fma_f32 v[88:89], v[8:9], v[0:1], v[4:5] op_sel_hi:[1,0,1]
	v_pk_fma_f32 v[90:91], v[10:11], v[0:1], v[6:7] op_sel_hi:[1,0,1]
	v_pk_fma_f32 v[18:19], v[8:9], v[66:67], v[18:19] op_sel_hi:[1,0,1]
	v_pk_fma_f32 v[20:21], v[10:11], v[66:67], v[20:21] op_sel_hi:[1,0,1]
	s_mov_b64 s[8:9], 0x18000
	s_waitcnt vmcnt(2)
	v_pk_fma_f32 v[34:35], v[100:101], v[38:39], v[34:35] op_sel:[0,1,0]
	v_pk_fma_f32 v[38:39], v[102:103], v[38:39], v[62:63] op_sel:[0,1,0]
	v_pk_fma_f32 v[62:63], v[100:101], v[42:43], v[74:75] op_sel:[0,1,0]
	v_pk_fma_f32 v[42:43], v[102:103], v[42:43], v[82:83] op_sel:[0,1,0]
	v_pk_fma_f32 v[74:75], v[100:101], v[46:47], v[64:65] op_sel:[0,1,0]
	v_pk_fma_f32 v[36:37], v[102:103], v[46:47], v[36:37] op_sel:[0,1,0]
	v_pk_fma_f32 v[46:47], v[100:101], v[50:51], v[30:31] op_sel:[0,1,0]
	v_pk_fma_f32 v[50:51], v[102:103], v[50:51], v[32:33] op_sel:[0,1,0]
	v_pk_fma_f32 v[82:83], v[100:101], v[54:55], v[26:27] op_sel:[0,1,0]
	v_pk_fma_f32 v[54:55], v[102:103], v[54:55], v[28:29] op_sel:[0,1,0]
	v_pk_fma_f32 v[92:93], v[100:101], v[58:59], v[22:23] op_sel:[0,1,0]
	v_pk_fma_f32 v[58:59], v[102:103], v[58:59], v[24:25] op_sel:[0,1,0]
	v_pk_fma_f32 v[94:95], v[100:101], v[66:67], v[18:19] op_sel:[0,1,0]
	v_pk_fma_f32 v[96:97], v[102:103], v[66:67], v[20:21] op_sel:[0,1,0]
	v_pk_fma_f32 v[84:85], v[100:101], v[70:71], v[84:85] op_sel:[0,1,0]
	v_pk_fma_f32 v[70:71], v[102:103], v[70:71], v[86:87] op_sel:[0,1,0]
	v_pk_fma_f32 v[64:65], v[100:101], v[0:1], v[88:89] op_sel:[0,1,0]
	v_pk_fma_f32 v[66:67], v[102:103], v[0:1], v[90:91] op_sel:[0,1,0]
	s_waitcnt vmcnt(1)
	v_pk_fma_f32 v[0:1], v[104:105], v[40:41], v[34:35] op_sel_hi:[1,0,1]
	v_pk_fma_f32 v[18:19], v[106:107], v[40:41], v[38:39] op_sel_hi:[1,0,1]
	v_mov_b32_e32 v24, v41
	v_pk_fma_f32 v[20:21], v[104:105], v[44:45], v[62:63] op_sel_hi:[1,0,1]
	v_pk_fma_f32 v[22:23], v[106:107], v[44:45], v[42:43] op_sel_hi:[1,0,1]
	v_mov_b32_e32 v30, v45
	v_pk_fma_f32 v[26:27], v[104:105], v[48:49], v[74:75] op_sel_hi:[1,0,1]
	v_pk_fma_f32 v[28:29], v[106:107], v[48:49], v[36:37] op_sel_hi:[1,0,1]
	v_mov_b32_e32 v36, v49
	v_pk_fma_f32 v[32:33], v[104:105], v[52:53], v[46:47] op_sel_hi:[1,0,1]
	v_pk_fma_f32 v[34:35], v[106:107], v[52:53], v[50:51] op_sel_hi:[1,0,1]
	v_mov_b32_e32 v42, v53
	v_pk_fma_f32 v[38:39], v[104:105], v[56:57], v[82:83] op_sel_hi:[1,0,1]
	v_pk_fma_f32 v[40:41], v[106:107], v[56:57], v[54:55] op_sel_hi:[1,0,1]
	v_mov_b32_e32 v48, v57
	v_pk_fma_f32 v[44:45], v[104:105], v[60:61], v[92:93] op_sel_hi:[1,0,1]
	v_pk_fma_f32 v[46:47], v[106:107], v[60:61], v[58:59] op_sel_hi:[1,0,1]
	v_mov_b32_e32 v54, v61
	v_pk_fma_f32 v[50:51], v[104:105], v[68:69], v[94:95] op_sel_hi:[1,0,1]
	v_pk_fma_f32 v[52:53], v[106:107], v[68:69], v[96:97] op_sel_hi:[1,0,1]
	v_mov_b32_e32 v58, v69
	v_mov_b32_e32 v56, v73
	v_pk_fma_f32 v[60:61], v[104:105], v[72:73], v[84:85] op_sel_hi:[1,0,1]
	v_pk_fma_f32 v[62:63], v[106:107], v[72:73], v[70:71] op_sel_hi:[1,0,1]
	v_pk_fma_f32 v[4:5], v[104:105], v[2:3], v[64:65] op_sel_hi:[1,0,1]
	v_pk_fma_f32 v[6:7], v[106:107], v[2:3], v[66:67] op_sel_hi:[1,0,1]
	v_mov_b32_e32 v74, v3
	v_lshl_add_u64 v[16:17], v[16:17], 0, s[8:9]
	s_waitcnt vmcnt(0)
	v_pk_fma_f32 v[66:67], v[108:109], v[24:25], v[0:1] op_sel_hi:[1,0,1]
	v_pk_fma_f32 v[72:73], v[110:111], v[24:25], v[18:19] op_sel_hi:[1,0,1]
	v_pk_fma_f32 v[68:69], v[108:109], v[30:31], v[20:21] op_sel_hi:[1,0,1]
	v_pk_fma_f32 v[70:71], v[110:111], v[30:31], v[22:23] op_sel_hi:[1,0,1]
	v_pk_fma_f32 v[64:65], v[108:109], v[36:37], v[26:27] op_sel_hi:[1,0,1]
	v_pk_fma_f32 v[36:37], v[110:111], v[36:37], v[28:29] op_sel_hi:[1,0,1]
	v_pk_fma_f32 v[30:31], v[108:109], v[42:43], v[32:33] op_sel_hi:[1,0,1]
	v_pk_fma_f32 v[32:33], v[110:111], v[42:43], v[34:35] op_sel_hi:[1,0,1]
	v_pk_fma_f32 v[26:27], v[108:109], v[48:49], v[38:39] op_sel_hi:[1,0,1]
	v_pk_fma_f32 v[28:29], v[110:111], v[48:49], v[40:41] op_sel_hi:[1,0,1]
	v_pk_fma_f32 v[22:23], v[108:109], v[54:55], v[44:45] op_sel_hi:[1,0,1]
	v_pk_fma_f32 v[24:25], v[110:111], v[54:55], v[46:47] op_sel_hi:[1,0,1]
	v_pk_fma_f32 v[18:19], v[108:109], v[58:59], v[50:51] op_sel_hi:[1,0,1]
	v_pk_fma_f32 v[20:21], v[110:111], v[58:59], v[52:53] op_sel_hi:[1,0,1]
	v_pk_fma_f32 v[0:1], v[108:109], v[56:57], v[60:61] op_sel_hi:[1,0,1]
	v_pk_fma_f32 v[2:3], v[110:111], v[56:57], v[62:63] op_sel_hi:[1,0,1]
	v_pk_fma_f32 v[4:5], v[108:109], v[74:75], v[4:5] op_sel_hi:[1,0,1]
	v_pk_fma_f32 v[6:7], v[110:111], v[74:75], v[6:7] op_sel_hi:[1,0,1]
	s_cbranch_scc1 .LBB0_440
	ds_bpermute_b32 v62, v78, v66
	ds_bpermute_b32 v63, v78, v67
	ds_bpermute_b32 v74, v78, v72
	ds_bpermute_b32 v75, v78, v73
	ds_bpermute_b32 v58, v78, v68
	ds_bpermute_b32 v59, v78, v69
	ds_bpermute_b32 v60, v78, v70
	ds_bpermute_b32 v61, v78, v71
	ds_bpermute_b32 v54, v78, v64
	ds_bpermute_b32 v55, v78, v65
	ds_bpermute_b32 v56, v78, v36
	ds_bpermute_b32 v57, v78, v37
	ds_bpermute_b32 v50, v78, v30
	ds_bpermute_b32 v51, v78, v31
	ds_bpermute_b32 v52, v78, v32
	ds_bpermute_b32 v53, v78, v33
	ds_bpermute_b32 v46, v78, v26
	ds_bpermute_b32 v47, v78, v27
	ds_bpermute_b32 v48, v78, v28
	ds_bpermute_b32 v49, v78, v29
	ds_bpermute_b32 v42, v78, v22
	ds_bpermute_b32 v43, v78, v23
	ds_bpermute_b32 v44, v78, v24
	ds_bpermute_b32 v45, v78, v25
	ds_bpermute_b32 v38, v78, v18
	ds_bpermute_b32 v39, v78, v19
	ds_bpermute_b32 v40, v78, v20
	ds_bpermute_b32 v41, v78, v21
	ds_bpermute_b32 v16, v78, v0
	ds_bpermute_b32 v17, v78, v1
	ds_bpermute_b32 v34, v78, v2
	ds_bpermute_b32 v35, v78, v3
	ds_bpermute_b32 v8, v78, v4
	ds_bpermute_b32 v9, v78, v5
	ds_bpermute_b32 v10, v78, v6
	ds_bpermute_b32 v11, v78, v7
	s_and_saveexec_b64 s[4:5], vcc
	s_cbranch_execz .LBB0_443
	s_waitcnt lgkmcnt(6)
	v_pk_add_f32 v[0:1], v[0:1], v[16:17]
	s_waitcnt lgkmcnt(4)
	v_pk_add_f32 v[2:3], v[2:3], v[34:35]
	v_pk_add_f32 v[82:83], v[66:67], v[62:63]
	v_pk_add_f32 v[84:85], v[72:73], v[74:75]
	v_pk_add_f32 v[58:59], v[68:69], v[58:59]
	v_pk_add_f32 v[60:61], v[70:71], v[60:61]
	v_pk_add_f32 v[54:55], v[64:65], v[54:55]
	v_pk_add_f32 v[56:57], v[36:37], v[56:57]
	v_pk_add_f32 v[30:31], v[30:31], v[50:51]
	v_pk_add_f32 v[32:33], v[32:33], v[52:53]
	v_pk_add_f32 v[26:27], v[26:27], v[46:47]
	v_pk_add_f32 v[28:29], v[28:29], v[48:49]
	v_pk_add_f32 v[22:23], v[22:23], v[42:43]
	v_pk_add_f32 v[24:25], v[24:25], v[44:45]
	v_pk_add_f32 v[18:19], v[18:19], v[38:39]
	v_pk_add_f32 v[20:21], v[20:21], v[40:41]
	ds_write_b128 v79, v[0:3] offset:3584
	s_waitcnt lgkmcnt(3)
	v_pk_add_f32 v[0:1], v[4:5], v[8:9]
	s_waitcnt lgkmcnt(1)
	v_pk_add_f32 v[2:3], v[6:7], v[10:11]
	ds_write_b128 v79, v[82:85]
	ds_write_b128 v79, v[58:61] offset:512
	ds_write_b128 v79, v[54:57] offset:1024
	ds_write_b128 v79, v[30:33] offset:1536
	ds_write_b128 v79, v[26:29] offset:2048
	ds_write_b128 v79, v[22:25] offset:2560
	ds_write_b128 v79, v[18:21] offset:3072
	ds_write_b128 v79, v[0:3] offset:4096
